# P6 (row rstd) computed per CU for its own P7 row panel; the P6->P7 grid barrier replaced by a workgroup barrier (no cross-CU dependency left)
# speedup vs baseline: 1.0021x; 1.0019x over previous
.LBB0_1090:
	s_cmp_le_i32 s28, s34
	s_cselect_b64 s[0:1], -1, 0
	s_and_b64 s[12:13], s[0:1], s[6:7]
	v_readlane_b32 s0, v255, 2
	s_add_i32 s0, s0, 7
	s_cmp_lt_i32 s0, s29
	s_cselect_b64 s[6:7], -1, 0
	s_andn2_b64 vcc, exec, s[12:13]
	s_cbranch_vccnz .LBB0_1148
	v_mov_b32_e32 v1, v0
	v_readlane_b32 s1, v252, 2
	s_mov_b64 s[14:15], s[72:73]
	s_nop 0
	s_and_b32 s1, s82, 7
	s_lshl_b32 s1, s1, 3
	s_bfe_u32 s0, s82, 0x30003
	s_add_i32 s1, s1, s0
	s_lshl_b32 s1, s1, 8
	v_and_b32_e32 v4, 0xff, v1
	v_add_u32_e32 v4, s1, v4
	s_movk_i32 s1, 0x4000
	v_cmp_gt_i32_e32 vcc, s1, v4
	s_and_saveexec_b64 s[12:13], vcc
	v_readlane_b32 s18, v254, 60
	s_movk_i32 s1, 0x3fff
	s_mov_b64 s[24:25], 0x5b0000c0
	v_readlane_b32 s19, v254, 61
	s_cbranch_execz .LBB0_1094
	s_load_dwordx2 s[16:17], s[14:15], 0x98
	s_waitcnt lgkmcnt(0)
	v_ashrrev_i32_e32 v5, 31, v4
	s_waitcnt vmcnt(0)
	v_mov_b64_e32 v[6:7], 0x5b400000
	v_lshl_add_u64 v[6:7], v[4:5], 2, v[6:7]
	v_lshlrev_b64 v[8:9], 8, v[4:5]
	s_mov_b64 s[22:23], 0

.LBB0_1094:
	s_or_b64 exec, exec, s[12:13]
	s_andn2_b64 vcc, exec, s[6:7]
	s_cbranch_vccnz .LBB0_1148
	s_waitcnt vmcnt(0)
	s_waitcnt lgkmcnt(0)
	s_barrier
	s_branch .LBB0_1148
	s_cbranch_execz .LBB0_1147
	v_readlane_b32 s1, v254, 15
	s_waitcnt vmcnt(0) expcnt(0) lgkmcnt(0)
	s_nop 0
	v_mov_b32_e32 v1, s1
	ds_read_b32 v4, v1
	v_readlane_b32 s1, v254, 16
	s_waitcnt lgkmcnt(0)
	v_cmp_ne_u32_e32 vcc, 0, v4
	v_mov_b32_e32 v1, s1
	ds_read_b32 v2, v1
	s_cbranch_vccnz .LBB0_1111
	v_readlane_b32 s16, v252, 0
	v_readlane_b32 s17, v252, 1
	s_load_dwordx2 s[14:15], s[16:17], 0x4
	s_mov_b32 s3, 1
	s_waitcnt lgkmcnt(0)
	s_mul_i32 s1, s14, s78
	s_mul_i32 s1, s1, s15
	s_branch .LBB0_1099
